# bar2
# speedup vs baseline: 1.0217x; 1.0098x over previous
; #define PG8_STAGE(bufoff, gbase, voff) do { _Pragma("unroll") for (int _i = 0; _i < 2; ++_i) \
;         __builtin_amdgcn_global_load_lds((const unsigned*)((const char*)(gbase) + (voff)[_i]), (LAS unsigned*)(lds + (bufoff) + ldsw + _i * 8192), 16, 0, 0); } while (0)
; #define PG8_LDA(dst, b, h) do { _Pragma("unroll") for (int m = 0; m < 4; ++m) _Pragma("unroll") for (int k = 0; k < 2; ++k) dst[m][k] = *(const LAS bf16x8*)(lds + PG8_SA(b, h) + aoff + m * 2048 + k * 1024); } while (0)
; #define PG8_LDB(dst, b, h) do { _Pragma("unroll") for (int n = 0; n < 2; ++n) _Pragma("unroll") for (int k = 0; k < 2; ++k) dst[n][k] = *(const LAS bf16x8*)(lds + PG8_SB(b, h) + boff + n * 2048 + k * 1024); } while (0)
; #define PG8_MMA(ai, bj, At, Bt) do { __builtin_amdgcn_s_setprio(1); _Pragma("unroll") for (int m = 0; m < 4; ++m) _Pragma("unroll") for (int n = 0; n < 2; ++n) _Pragma("unroll") for (int k = 0; k < 2; ++k) \
;         acc[ai][bj][m][n] = __builtin_amdgcn_mfma_f32_16x16x32_bf16(Bt[n][k], At[m][k], acc[ai][bj][m][n], 0, 0, 0); __builtin_amdgcn_s_setprio(0); } while (0)
; #define PG8_WAIT_V(n) asm volatile("s_waitcnt vmcnt(" #n ")" ::: "memory")
; #define PG8_WAIT_L(n) asm volatile("s_waitcnt lgkmcnt(" #n ")" ::: "memory")
; #define PG8_BAR __builtin_amdgcn_s_barrier()
; template <class Epi, class Job>
; __device__ __forceinline__ void gemm_phase(LAS unsigned char* lds, const Job& S, const Epi& E) {
;     ...
;             const bool last = (t == nt - 2);
;             const char* a1 = cA + (size_t)(t + 1) * kstep;
;             const char* a2 = last ? nA : cA + (size_t)(t + 2) * kstep; const char* b2 = last ? nB : cB + (size_t)(t + 2) * kstep;
;             const char* a3 = a2 + kstep; const char* b3 = b2 + kstep;
;             PG8_LDB(B0, 0, 0); PG8_SCHED; PG8_LDA(At, 0, 0); PG8_STAGE(PG8_SA(1, 1), a1 + hstepA, voffA);
;             PG8_WAIT_L(8); PG8_BAR; PG8_WAIT_L(0); PG8_MMA(0, 0, At, B0); PG8_BAR; PG8_SCHED;
;             PG8_LDB(B1, 0, 1); PG8_STAGE(PG8_SB(0, 0), b2, voffB);
;             PG8_BAR; PG8_WAIT_L(0); PG8_MMA(0, 1, At, B1); PG8_BAR;
;             PG8_LDA(At, 0, 1); PG8_STAGE(PG8_SA(0, 0), a2, voffA);
;             PG8_BAR; PG8_WAIT_L(0); PG8_MMA(1, 0, At, B0); PG8_BAR; PG8_SCHED;
;             PG8_STAGE(PG8_SB(0, 1), b2 + hstepB, voffB);
;             PG8_WAIT_V(6); PG8_BAR; PG8_MMA(1, 1, At, B1); PG8_BAR;
.LBB0_186:
	s_add_i32 m0, s52, 0xc000
	s_nop 0
	global_load_lds_dwordx4 v144, s[28:29]
	s_add_i32 m0, s52, 0xe000
	s_nop 0
	global_load_lds_dwordx4 v146, s[28:29]
	s_add_u32 s36, s28, 0xfff00080
	s_addc_u32 s37, s29, -1
	s_cmp_eq_u32 s68, 60
	s_cselect_b32 s47, s23, s37
	s_cselect_b32 s46, s22, s36
	s_cselect_b32 s37, s25, s67
	s_cselect_b32 s36, s24, s27
	ds_read_b128 v[190:193], v155 offset:1024
	ds_read_b128 v[198:201], v155 offset:3072
	ds_read_b128 v[206:209], v155 offset:5120
	ds_read_b128 v[214:217], v155 offset:7168
	s_waitcnt lgkmcnt(8)
	s_waitcnt lgkmcnt(0)
	s_setprio 1
	s_barrier
	v_mfma_f32_16x16x32_bf16 v[124:127], v[158:161], v[186:189], v[124:127]
	ds_read_b128 v[218:221], v156
	v_mfma_f32_16x16x32_bf16 v[120:123], v[178:181], v[186:189], v[120:123]
	v_mfma_f32_16x16x32_bf16 v[112:115], v[158:161], v[194:197], v[112:115]
	ds_read_b128 v[222:225], v156 offset:1024
	v_mfma_f32_16x16x32_bf16 v[104:107], v[178:181], v[194:197], v[104:107]
	v_mfma_f32_16x16x32_bf16 v[100:103], v[158:161], v[202:205], v[100:103]
	ds_read_b128 v[226:229], v156 offset:2048
	v_mfma_f32_16x16x32_bf16 v[92:95], v[178:181], v[202:205], v[92:95]
	v_mfma_f32_16x16x32_bf16 v[84:87], v[158:161], v[210:213], v[84:87]
	ds_read_b128 v[230:233], v156 offset:3072
	v_mfma_f32_16x16x32_bf16 v[76:79], v[178:181], v[210:213], v[76:79]
	v_mfma_f32_16x16x32_bf16 v[124:127], v[174:177], v[190:193], v[124:127]
	v_mfma_f32_16x16x32_bf16 v[120:123], v[182:185], v[190:193], v[120:123]
	v_mfma_f32_16x16x32_bf16 v[112:115], v[174:177], v[198:201], v[112:115]
	v_mfma_f32_16x16x32_bf16 v[104:107], v[182:185], v[198:201], v[104:107]
	v_mfma_f32_16x16x32_bf16 v[100:103], v[174:177], v[206:209], v[100:103]
	v_mfma_f32_16x16x32_bf16 v[92:95], v[182:185], v[206:209], v[92:95]
	v_mfma_f32_16x16x32_bf16 v[84:87], v[174:177], v[214:217], v[84:87]
	v_mfma_f32_16x16x32_bf16 v[76:79], v[182:185], v[214:217], v[76:79]
	s_barrier
	s_setprio 0
	s_add_i32 s69, s60, s49
	s_mov_b32 m0, s69
	s_nop 0
	global_load_lds_dwordx4 v136, s[36:37]
	s_add_i32 m0, s69, 0x2000
	s_nop 0
	global_load_lds_dwordx4 v140, s[36:37]
	s_waitcnt lgkmcnt(0)
	s_setprio 1
	s_barrier
	v_mfma_f32_16x16x32_bf16 v[116:119], v[218:221], v[186:189], v[116:119]
	v_mfma_f32_16x16x32_bf16 v[108:111], v[226:229], v[186:189], v[108:111]
	v_mfma_f32_16x16x32_bf16 v[96:99], v[218:221], v[194:197], v[96:99]
	v_mfma_f32_16x16x32_bf16 v[88:91], v[226:229], v[194:197], v[88:91]
	v_mfma_f32_16x16x32_bf16 v[80:83], v[218:221], v[202:205], v[80:83]
	v_mfma_f32_16x16x32_bf16 v[72:75], v[226:229], v[202:205], v[72:75]
	v_mfma_f32_16x16x32_bf16 v[68:71], v[218:221], v[210:213], v[68:71]
	v_mfma_f32_16x16x32_bf16 v[64:67], v[226:229], v[210:213], v[64:67]
	v_mfma_f32_16x16x32_bf16 v[116:119], v[222:225], v[190:193], v[116:119]
	ds_read_b128 v[186:189], v155 offset:16384
	v_mfma_f32_16x16x32_bf16 v[108:111], v[230:233], v[190:193], v[108:111]
	v_mfma_f32_16x16x32_bf16 v[96:99], v[222:225], v[198:201], v[96:99]
	ds_read_b128 v[194:197], v155 offset:18432
	v_mfma_f32_16x16x32_bf16 v[88:91], v[230:233], v[198:201], v[88:91]
	v_mfma_f32_16x16x32_bf16 v[80:83], v[222:225], v[206:209], v[80:83]
	ds_read_b128 v[202:205], v155 offset:20480
	v_mfma_f32_16x16x32_bf16 v[72:75], v[230:233], v[206:209], v[72:75]
	v_mfma_f32_16x16x32_bf16 v[68:71], v[222:225], v[214:217], v[68:71]
	ds_read_b128 v[210:213], v155 offset:22528
	v_mfma_f32_16x16x32_bf16 v[64:67], v[230:233], v[214:217], v[64:67]
	s_barrier
	s_setprio 0
	s_mov_b32 m0, s52
	s_mov_b64 s[100:101], s[46:47]
	global_load_lds_dwordx4 v134, s[46:47]
	s_mov_b32 m0, s53
	s_nop 0
	global_load_lds_dwordx4 v138, s[46:47]
	ds_read_b128 v[190:193], v155 offset:17408
	ds_read_b128 v[198:201], v155 offset:19456
	ds_read_b128 v[206:209], v155 offset:21504
	ds_read_b128 v[214:217], v155 offset:23552
	s_waitcnt vmcnt(8)
	s_waitcnt lgkmcnt(0)
	s_setprio 1
	s_barrier
	v_mfma_f32_16x16x32_bf16 v[60:63], v[158:161], v[186:189], v[60:63]
	v_mfma_f32_16x16x32_bf16 v[56:59], v[178:181], v[186:189], v[56:59]
	v_mfma_f32_16x16x32_bf16 v[52:55], v[158:161], v[194:197], v[52:55]
	v_mfma_f32_16x16x32_bf16 v[44:47], v[178:181], v[194:197], v[44:47]
	v_mfma_f32_16x16x32_bf16 v[36:39], v[158:161], v[202:205], v[36:39]
	v_mfma_f32_16x16x32_bf16 v[28:31], v[178:181], v[202:205], v[28:31]
	v_mfma_f32_16x16x32_bf16 v[20:23], v[158:161], v[210:213], v[20:23]
	v_mfma_f32_16x16x32_bf16 v[12:15], v[178:181], v[210:213], v[12:15]
	v_mfma_f32_16x16x32_bf16 v[60:63], v[174:177], v[190:193], v[60:63]
	v_mfma_f32_16x16x32_bf16 v[56:59], v[182:185], v[190:193], v[56:59]
	v_mfma_f32_16x16x32_bf16 v[52:55], v[174:177], v[198:201], v[52:55]
	v_mfma_f32_16x16x32_bf16 v[44:47], v[182:185], v[198:201], v[44:47]
	v_mfma_f32_16x16x32_bf16 v[36:39], v[174:177], v[206:209], v[36:39]
	v_mfma_f32_16x16x32_bf16 v[28:31], v[182:185], v[206:209], v[28:31]
	v_mfma_f32_16x16x32_bf16 v[20:23], v[174:177], v[214:217], v[20:23]
	v_mfma_f32_16x16x32_bf16 v[12:15], v[182:185], v[214:217], v[12:15]
	s_barrier
	s_setprio 0
	s_add_u32 s70, s36, 0x100000
	s_addc_u32 s71, s37, 0
	s_add_i32 s69, s61, s49
	s_mov_b32 m0, s69
	s_nop 0
	global_load_lds_dwordx4 v136, s[70:71]
	s_add_i32 m0, s69, 0x2000
	s_nop 0
	global_load_lds_dwordx4 v140, s[70:71]
	s_waitcnt vmcnt(6)
	s_setprio 1
	v_add_u32_e32 v157, 0x18000, v153
	s_barrier
; #define PG8_STAGE(bufoff, gbase, voff) do { _Pragma("unroll") for (int _i = 0; _i < 2; ++_i) \
;         __builtin_amdgcn_global_load_lds((const unsigned*)((const char*)(gbase) + (voff)[_i]), (LAS unsigned*)(lds + (bufoff) + ldsw + _i * 8192), 16, 0, 0); } while (0)
; #define PG8_LDA(dst, b, h) do { _Pragma("unroll") for (int m = 0; m < 4; ++m) _Pragma("unroll") for (int k = 0; k < 2; ++k) dst[m][k] = *(const LAS bf16x8*)(lds + PG8_SA(b, h) + aoff + m * 2048 + k * 1024); } while (0)
; #define PG8_LDB(dst, b, h) do { _Pragma("unroll") for (int n = 0; n < 2; ++n) _Pragma("unroll") for (int k = 0; k < 2; ++k) dst[n][k] = *(const LAS bf16x8*)(lds + PG8_SB(b, h) + boff + n * 2048 + k * 1024); } while (0)
; #define PG8_MMA(ai, bj, At, Bt) do { __builtin_amdgcn_s_setprio(1); _Pragma("unroll") for (int m = 0; m < 4; ++m) _Pragma("unroll") for (int n = 0; n < 2; ++n) _Pragma("unroll") for (int k = 0; k < 2; ++k) \
;         acc[ai][bj][m][n] = __builtin_amdgcn_mfma_f32_16x16x32_bf16(Bt[n][k], At[m][k], acc[ai][bj][m][n], 0, 0, 0); __builtin_amdgcn_s_setprio(0); } while (0)
; #define PG8_WAIT_V(n) asm volatile("s_waitcnt vmcnt(" #n ")" ::: "memory")
; #define PG8_WAIT_L(n) asm volatile("s_waitcnt lgkmcnt(" #n ")" ::: "memory")
; #define PG8_BAR __builtin_amdgcn_s_barrier()
; #define PG8_SCHED __builtin_amdgcn_sched_barrier(0)
; template <class Epi, class Job>
; __device__ __forceinline__ void gemm_phase(LAS unsigned char* lds, const Job& S, const Epi& E) {
;     ...
;             PG8_WAIT_V(6); PG8_BAR; PG8_MMA(1, 1, At, B1); PG8_BAR;
;             PG8_LDB(B0, 1, 0); PG8_SCHED; PG8_LDA(At, 1, 0); PG8_STAGE(PG8_SA(0, 1), a2 + hstepA, voffA);
;             PG8_WAIT_L(8); PG8_BAR; PG8_WAIT_L(0); PG8_MMA(0, 0, At, B0); PG8_BAR; PG8_SCHED;
;             PG8_LDB(B1, 1, 1); PG8_STAGE(PG8_SB(1, 0), b3, voffB);
;             PG8_BAR; PG8_WAIT_L(0); PG8_MMA(0, 1, At, B1); PG8_BAR;
	v_mfma_f32_16x16x32_bf16 v[48:51], v[218:221], v[186:189], v[48:51]
	ds_read_b128 v[158:161], v157
	v_mfma_f32_16x16x32_bf16 v[40:43], v[226:229], v[186:189], v[40:43]
	v_mfma_f32_16x16x32_bf16 v[32:35], v[218:221], v[194:197], v[32:35]
	ds_read_b128 v[174:177], v157 offset:1024
	v_mfma_f32_16x16x32_bf16 v[24:27], v[226:229], v[194:197], v[24:27]
	v_mfma_f32_16x16x32_bf16 v[16:19], v[218:221], v[202:205], v[16:19]
	ds_read_b128 v[178:181], v157 offset:2048
	v_mfma_f32_16x16x32_bf16 v[8:11], v[226:229], v[202:205], v[8:11]
	v_mfma_f32_16x16x32_bf16 v[4:7], v[218:221], v[210:213], v[4:7]
	ds_read_b128 v[182:185], v157 offset:3072
	v_mfma_f32_16x16x32_bf16 v[0:3], v[226:229], v[210:213], v[0:3]
	v_mfma_f32_16x16x32_bf16 v[48:51], v[222:225], v[190:193], v[48:51]
	ds_read_b128 v[186:189], v155 offset:32768
	v_mfma_f32_16x16x32_bf16 v[40:43], v[230:233], v[190:193], v[40:43]
	v_mfma_f32_16x16x32_bf16 v[32:35], v[222:225], v[198:201], v[32:35]
	ds_read_b128 v[194:197], v155 offset:34816
	v_mfma_f32_16x16x32_bf16 v[24:27], v[230:233], v[198:201], v[24:27]
	v_mfma_f32_16x16x32_bf16 v[16:19], v[222:225], v[206:209], v[16:19]
	ds_read_b128 v[202:205], v155 offset:36864
	v_mfma_f32_16x16x32_bf16 v[8:11], v[230:233], v[206:209], v[8:11]
	v_mfma_f32_16x16x32_bf16 v[4:7], v[222:225], v[214:217], v[4:7]
	ds_read_b128 v[210:213], v155 offset:38912
	v_mfma_f32_16x16x32_bf16 v[0:3], v[230:233], v[214:217], v[0:3]
	s_barrier
	s_setprio 0
	s_add_i32 s69, 0, 0x18000
	v_add_u32_e32 v157, s69, v153
	s_add_u32 s46, s46, 0x100000
	s_addc_u32 s47, s47, 0
	s_mov_b32 m0, s54
	s_nop 0
	global_load_lds_dwordx4 v134, s[46:47]
	s_mov_b32 m0, s55
	s_nop 0
	global_load_lds_dwordx4 v138, s[46:47]
	ds_read_b128 v[190:193], v155 offset:33792
	ds_read_b128 v[198:201], v155 offset:35840
	ds_read_b128 v[206:209], v155 offset:37888
	ds_read_b128 v[214:217], v155 offset:39936
	s_waitcnt lgkmcnt(8)
	s_waitcnt lgkmcnt(0)
	s_setprio 1
	v_add_u32_e32 v157, 0x1c000, v153
	s_barrier
	v_mfma_f32_16x16x32_bf16 v[124:127], v[158:161], v[186:189], v[124:127]
	ds_read_b128 v[218:221], v157
	v_mfma_f32_16x16x32_bf16 v[120:123], v[178:181], v[186:189], v[120:123]
	v_mfma_f32_16x16x32_bf16 v[112:115], v[158:161], v[194:197], v[112:115]
	ds_read_b128 v[222:225], v157 offset:1024
	v_mfma_f32_16x16x32_bf16 v[104:107], v[178:181], v[194:197], v[104:107]
	v_mfma_f32_16x16x32_bf16 v[100:103], v[158:161], v[202:205], v[100:103]
	ds_read_b128 v[226:229], v157 offset:2048
	v_mfma_f32_16x16x32_bf16 v[92:95], v[178:181], v[202:205], v[92:95]
	v_mfma_f32_16x16x32_bf16 v[84:87], v[158:161], v[210:213], v[84:87]
	ds_read_b128 v[230:233], v157 offset:3072
	v_mfma_f32_16x16x32_bf16 v[76:79], v[178:181], v[210:213], v[76:79]
	v_mfma_f32_16x16x32_bf16 v[124:127], v[174:177], v[190:193], v[124:127]
	v_mfma_f32_16x16x32_bf16 v[120:123], v[182:185], v[190:193], v[120:123]
	v_mfma_f32_16x16x32_bf16 v[112:115], v[174:177], v[198:201], v[112:115]
	v_mfma_f32_16x16x32_bf16 v[104:107], v[182:185], v[198:201], v[104:107]
	v_mfma_f32_16x16x32_bf16 v[100:103], v[174:177], v[206:209], v[100:103]
	v_mfma_f32_16x16x32_bf16 v[92:95], v[182:185], v[206:209], v[92:95]
	v_mfma_f32_16x16x32_bf16 v[84:87], v[174:177], v[214:217], v[84:87]
	v_mfma_f32_16x16x32_bf16 v[76:79], v[182:185], v[214:217], v[76:79]
	s_barrier
	s_setprio 0
	s_add_i32 s46, 0, 0x1c000
	s_add_i32 s47, s69, s49
	v_add_u32_e32 v157, s46, v153
	s_add_u32 s98, s36, s10
	s_addc_u32 s99, s37, s11
	s_mov_b32 m0, s47
	s_nop 0
	global_load_lds_dwordx4 v136, s[98:99]
	s_add_i32 m0, s47, 0x2000
	s_nop 0
	global_load_lds_dwordx4 v140, s[98:99]
	s_waitcnt lgkmcnt(0)
	s_setprio 1
	s_barrier
	v_mfma_f32_16x16x32_bf16 v[116:119], v[218:221], v[186:189], v[116:119]
	v_mfma_f32_16x16x32_bf16 v[108:111], v[226:229], v[186:189], v[108:111]
	v_mfma_f32_16x16x32_bf16 v[96:99], v[218:221], v[194:197], v[96:99]
	v_mfma_f32_16x16x32_bf16 v[88:91], v[226:229], v[194:197], v[88:91]
	v_mfma_f32_16x16x32_bf16 v[80:83], v[218:221], v[202:205], v[80:83]
	v_mfma_f32_16x16x32_bf16 v[72:75], v[226:229], v[202:205], v[72:75]
	v_mfma_f32_16x16x32_bf16 v[68:71], v[218:221], v[210:213], v[68:71]
	v_mfma_f32_16x16x32_bf16 v[64:67], v[226:229], v[210:213], v[64:67]
	v_mfma_f32_16x16x32_bf16 v[116:119], v[222:225], v[190:193], v[116:119]
	ds_read_b128 v[186:189], v155 offset:49152
	v_mfma_f32_16x16x32_bf16 v[108:111], v[230:233], v[190:193], v[108:111]
	v_mfma_f32_16x16x32_bf16 v[96:99], v[222:225], v[198:201], v[96:99]
	ds_read_b128 v[194:197], v155 offset:51200
	v_mfma_f32_16x16x32_bf16 v[88:91], v[230:233], v[198:201], v[88:91]
	v_mfma_f32_16x16x32_bf16 v[80:83], v[222:225], v[206:209], v[80:83]
	ds_read_b128 v[202:205], v155 offset:53248
	v_mfma_f32_16x16x32_bf16 v[72:75], v[230:233], v[206:209], v[72:75]
	v_mfma_f32_16x16x32_bf16 v[68:71], v[222:225], v[214:217], v[68:71]
	ds_read_b128 v[210:213], v155 offset:55296
	v_mfma_f32_16x16x32_bf16 v[64:67], v[230:233], v[214:217], v[64:67]
	s_barrier
; #define PG8_STAGE(bufoff, gbase, voff) do { _Pragma("unroll") for (int _i = 0; _i < 2; ++_i) \
;         __builtin_amdgcn_global_load_lds((const unsigned*)((const char*)(gbase) + (voff)[_i]), (LAS unsigned*)(lds + (bufoff) + ldsw + _i * 8192), 16, 0, 0); } while (0)
; #define PG8_LDA(dst, b, h) do { _Pragma("unroll") for (int m = 0; m < 4; ++m) _Pragma("unroll") for (int k = 0; k < 2; ++k) dst[m][k] = *(const LAS bf16x8*)(lds + PG8_SA(b, h) + aoff + m * 2048 + k * 1024); } while (0)
; #define PG8_MMA(ai, bj, At, Bt) do { __builtin_amdgcn_s_setprio(1); _Pragma("unroll") for (int m = 0; m < 4; ++m) _Pragma("unroll") for (int n = 0; n < 2; ++n) _Pragma("unroll") for (int k = 0; k < 2; ++k) \
;         acc[ai][bj][m][n] = __builtin_amdgcn_mfma_f32_16x16x32_bf16(Bt[n][k], At[m][k], acc[ai][bj][m][n], 0, 0, 0); __builtin_amdgcn_s_setprio(0); } while (0)
; #define PG8_WAIT_V(n) asm volatile("s_waitcnt vmcnt(" #n ")" ::: "memory")
; #define PG8_WAIT_L(n) asm volatile("s_waitcnt lgkmcnt(" #n ")" ::: "memory")
; #define PG8_BAR __builtin_amdgcn_s_barrier()
; #define PG8_SCHED __builtin_amdgcn_sched_barrier(0)
;     __device__ __forceinline__ void operator()(const f32x4 (&acc)[2][2][4][2], const Unit& u, int wr, int wc, int fr, int fq) const {
;     ...
;         if (u.ocol < 6144) { const int sect = u.ocol >> 11, hh0 = (u.ocol & 2047) >> 7, b = u.orow >= SEQ ? 1 : 0;
;             base = qkv + (size_t)sect * MTOK * 2048 + ((size_t)(b * 16 + hh0) * SEQ + (row0 & (SEQ - 1))) * 128 + wc * 32 + 8 * fq; rstride = 128; bjstride = (size_t)SEQ * 128; }
;         else { base = proj2 + (size_t)row0 * NP2 + (u.ocol - 6144) + wc * 32 + 8 * fq; rstride = NP2; bjstride = HALF; }
; template <class Epi, class Job>
; __device__ __forceinline__ void gemm_phase(LAS unsigned char* lds, const Job& S, const Epi& E) {
;     ...
;             PG8_LDA(At, 1, 1); PG8_STAGE(PG8_SA(1, 0), a3, voffA);
;             PG8_BAR; PG8_WAIT_L(0); PG8_MMA(1, 0, At, B0); PG8_BAR; PG8_SCHED;
;             PG8_STAGE(PG8_SB(1, 1), b3 + hstepB, voffB);
;             PG8_WAIT_V(6); PG8_BAR; PG8_MMA(1, 1, At, B1); PG8_BAR;
	s_setprio 0
	s_mov_b32 m0, s56
	s_add_u32 s100, s100, s10
	s_addc_u32 s101, s101, s11
	global_load_lds_dwordx4 v134, s[100:101]
	s_mov_b32 m0, s57
	s_nop 0
	global_load_lds_dwordx4 v138, s[100:101]
	ds_read_b128 v[190:193], v155 offset:50176
	ds_read_b128 v[198:201], v155 offset:52224
	ds_read_b128 v[206:209], v155 offset:54272
	ds_read_b128 v[214:217], v155 offset:56320
	s_waitcnt vmcnt(8)
	s_waitcnt lgkmcnt(0)
	s_setprio 1
	s_barrier
	v_mfma_f32_16x16x32_bf16 v[60:63], v[158:161], v[186:189], v[60:63]
	v_mfma_f32_16x16x32_bf16 v[56:59], v[178:181], v[186:189], v[56:59]
	v_mfma_f32_16x16x32_bf16 v[52:55], v[158:161], v[194:197], v[52:55]
	v_mfma_f32_16x16x32_bf16 v[44:47], v[178:181], v[194:197], v[44:47]
	v_mfma_f32_16x16x32_bf16 v[36:39], v[158:161], v[202:205], v[36:39]
	v_mfma_f32_16x16x32_bf16 v[28:31], v[178:181], v[202:205], v[28:31]
	v_mfma_f32_16x16x32_bf16 v[20:23], v[158:161], v[210:213], v[20:23]
	v_mfma_f32_16x16x32_bf16 v[12:15], v[178:181], v[210:213], v[12:15]
	v_mfma_f32_16x16x32_bf16 v[60:63], v[174:177], v[190:193], v[60:63]
	v_mfma_f32_16x16x32_bf16 v[56:59], v[182:185], v[190:193], v[56:59]
	v_mfma_f32_16x16x32_bf16 v[52:55], v[174:177], v[198:201], v[52:55]
	v_mfma_f32_16x16x32_bf16 v[44:47], v[182:185], v[198:201], v[44:47]
	v_mfma_f32_16x16x32_bf16 v[36:39], v[174:177], v[206:209], v[36:39]
	v_mfma_f32_16x16x32_bf16 v[28:31], v[182:185], v[206:209], v[28:31]
	v_mfma_f32_16x16x32_bf16 v[20:23], v[174:177], v[214:217], v[20:23]
	v_mfma_f32_16x16x32_bf16 v[12:15], v[182:185], v[214:217], v[12:15]
	s_barrier
	s_setprio 0
	s_add_u32 s36, s36, 0x100080
	s_addc_u32 s37, s37, 0
	s_add_i32 s46, s46, s49
	s_mov_b32 m0, s46
	s_nop 0
	global_load_lds_dwordx4 v136, s[36:37]
	s_add_i32 m0, s46, 0x2000
	s_nop 0
	global_load_lds_dwordx4 v140, s[36:37]
	s_waitcnt vmcnt(6)
	s_setprio 1
	s_barrier
	v_mfma_f32_16x16x32_bf16 v[48:51], v[218:221], v[186:189], v[48:51]
	ds_read_b128 v[158:161], v154
	v_mfma_f32_16x16x32_bf16 v[40:43], v[226:229], v[186:189], v[40:43]
	v_mfma_f32_16x16x32_bf16 v[32:35], v[218:221], v[194:197], v[32:35]
	ds_read_b128 v[174:177], v154 offset:1024
	v_mfma_f32_16x16x32_bf16 v[24:27], v[226:229], v[194:197], v[24:27]
	v_mfma_f32_16x16x32_bf16 v[16:19], v[218:221], v[202:205], v[16:19]
	ds_read_b128 v[178:181], v154 offset:2048
	v_mfma_f32_16x16x32_bf16 v[8:11], v[226:229], v[202:205], v[8:11]
	v_mfma_f32_16x16x32_bf16 v[4:7], v[218:221], v[210:213], v[4:7]
	ds_read_b128 v[182:185], v154 offset:3072
	v_mfma_f32_16x16x32_bf16 v[0:3], v[226:229], v[210:213], v[0:3]
	v_mfma_f32_16x16x32_bf16 v[48:51], v[222:225], v[190:193], v[48:51]
	ds_read_b128 v[186:189], v155
	v_mfma_f32_16x16x32_bf16 v[40:43], v[230:233], v[190:193], v[40:43]
	v_mfma_f32_16x16x32_bf16 v[32:35], v[222:225], v[198:201], v[32:35]
	ds_read_b128 v[194:197], v155 offset:2048
	v_mfma_f32_16x16x32_bf16 v[24:27], v[230:233], v[198:201], v[24:27]
	v_mfma_f32_16x16x32_bf16 v[16:19], v[222:225], v[206:209], v[16:19]
	ds_read_b128 v[202:205], v155 offset:4096
	v_mfma_f32_16x16x32_bf16 v[8:11], v[230:233], v[206:209], v[8:11]
	v_mfma_f32_16x16x32_bf16 v[4:7], v[222:225], v[214:217], v[4:7]
	ds_read_b128 v[210:213], v155 offset:6144
	v_mfma_f32_16x16x32_bf16 v[0:3], v[230:233], v[214:217], v[0:3]
	s_barrier
	s_setprio 0
	s_add_i32 s68, s68, 2
	s_add_u32 s28, s28, 0x100
	s_addc_u32 s29, s29, 0
	s_add_u32 s27, s27, 0x100
	s_addc_u32 s67, s67, 0
	s_cmp_gt_u32 s68, 61
	s_cbranch_scc0 .LBB0_186
	s_waitcnt lgkmcnt(0)
	v_add_u32_e32 v157, s66, v131
	s_cmpk_gt_i32 s26, 0x17ff
	s_mov_b64 s[28:29], -1
	s_cbranch_scc0 .LBB0_189
	v_mov_b64_e32 v[150:151], s[20:21]
	v_mad_i64_i32 v[150:151], s[28:29], v157, s62, v[150:151]
	s_mov_b32 s27, s9
	v_lshl_add_u64 v[150:151], s[26:27], 1, v[150:151]
	v_lshl_add_u64 v[150:151], v[150:151], 0, s[12:13]
	s_mov_b64 s[28:29], 0

; #define PG8_STAGE(bufoff, gbase, voff) do { _Pragma("unroll") for (int _i = 0; _i < 2; ++_i) \
;         __builtin_amdgcn_global_load_lds((const unsigned*)((const char*)(gbase) + (voff)[_i]), (LAS unsigned*)(lds + (bufoff) + ldsw + _i * 8192), 16, 0, 0); } while (0)
; #define PG8_LDA(dst, b, h) do { _Pragma("unroll") for (int m = 0; m < 4; ++m) _Pragma("unroll") for (int k = 0; k < 2; ++k) dst[m][k] = *(const LAS bf16x8*)(lds + PG8_SA(b, h) + aoff + m * 2048 + k * 1024); } while (0)
; #define PG8_LDB(dst, b, h) do { _Pragma("unroll") for (int n = 0; n < 2; ++n) _Pragma("unroll") for (int k = 0; k < 2; ++k) dst[n][k] = *(const LAS bf16x8*)(lds + PG8_SB(b, h) + boff + n * 2048 + k * 1024); } while (0)
; #define PG8_MMA(ai, bj, At, Bt) do { __builtin_amdgcn_s_setprio(1); _Pragma("unroll") for (int m = 0; m < 4; ++m) _Pragma("unroll") for (int n = 0; n < 2; ++n) _Pragma("unroll") for (int k = 0; k < 2; ++k) \
;         acc[ai][bj][m][n] = __builtin_amdgcn_mfma_f32_16x16x32_bf16(Bt[n][k], At[m][k], acc[ai][bj][m][n], 0, 0, 0); __builtin_amdgcn_s_setprio(0); } while (0)
; #define PG8_WAIT_V(n) asm volatile("s_waitcnt vmcnt(" #n ")" ::: "memory")
; #define PG8_WAIT_L(n) asm volatile("s_waitcnt lgkmcnt(" #n ")" ::: "memory")
; #define PG8_BAR __builtin_amdgcn_s_barrier()
; template <class Epi, class Job>
; __device__ __forceinline__ void gemm_phase(LAS unsigned char* lds, const Job& S, const Epi& E) {
;     ...
;             const bool last = (t == nt - 2);
;             const char* a1 = cA + (size_t)(t + 1) * kstep;
;             const char* a2 = last ? nA : cA + (size_t)(t + 2) * kstep; const char* b2 = last ? nB : cB + (size_t)(t + 2) * kstep;
;             const char* a3 = a2 + kstep; const char* b3 = b2 + kstep;
;             PG8_LDB(B0, 0, 0); PG8_SCHED; PG8_LDA(At, 0, 0); PG8_STAGE(PG8_SA(1, 1), a1 + hstepA, voffA);
;             PG8_WAIT_L(8); PG8_BAR; PG8_WAIT_L(0); PG8_MMA(0, 0, At, B0); PG8_BAR; PG8_SCHED;
;             PG8_LDB(B1, 0, 1); PG8_STAGE(PG8_SB(0, 0), b2, voffB);
;             PG8_BAR; PG8_WAIT_L(0); PG8_MMA(0, 1, At, B1); PG8_BAR;
;             PG8_LDA(At, 0, 1); PG8_STAGE(PG8_SA(0, 0), a2, voffA);
;             PG8_BAR; PG8_WAIT_L(0); PG8_MMA(1, 0, At, B0); PG8_BAR; PG8_SCHED;
;             PG8_STAGE(PG8_SB(0, 1), b2 + hstepB, voffB);
;             PG8_WAIT_V(6); PG8_BAR; PG8_MMA(1, 1, At, B1); PG8_BAR;
.LBB0_457:
	s_add_i32 m0, s57, 0xc000
	s_nop 0
	global_load_lds_dwordx4 v132, s[36:37]
	s_add_i32 m0, s57, 0xe000
	s_nop 0
	global_load_lds_dwordx4 v142, s[36:37]
	s_add_u32 s46, s36, 0xfff00080
	s_addc_u32 s47, s37, -1
	s_cmp_eq_u32 s81, 60
	s_cselect_b32 s49, s29, s47
	s_cselect_b32 s48, s28, s46
	s_cselect_b32 s47, s31, s80
	s_cselect_b32 s46, s30, s79
	ds_read_b128 v[174:177], v151 offset:1024
	ds_read_b128 v[182:185], v151 offset:3072
	ds_read_b128 v[190:193], v151 offset:5120
	ds_read_b128 v[198:201], v151 offset:7168
	s_waitcnt lgkmcnt(8)
	s_waitcnt lgkmcnt(0)
	s_setprio 1
	s_barrier
	v_mfma_f32_16x16x32_bf16 v[124:127], v[154:157], v[170:173], v[124:127]
	ds_read_b128 v[202:205], v152
	v_mfma_f32_16x16x32_bf16 v[120:123], v[162:165], v[170:173], v[120:123]
	v_mfma_f32_16x16x32_bf16 v[116:119], v[154:157], v[178:181], v[116:119]
	ds_read_b128 v[206:209], v152 offset:1024
	v_mfma_f32_16x16x32_bf16 v[108:111], v[162:165], v[178:181], v[108:111]
	v_mfma_f32_16x16x32_bf16 v[100:103], v[154:157], v[186:189], v[100:103]
	ds_read_b128 v[210:213], v152 offset:2048
	v_mfma_f32_16x16x32_bf16 v[92:95], v[162:165], v[186:189], v[92:95]
	v_mfma_f32_16x16x32_bf16 v[84:87], v[154:157], v[194:197], v[84:87]
	ds_read_b128 v[214:217], v152 offset:3072
	v_mfma_f32_16x16x32_bf16 v[76:79], v[162:165], v[194:197], v[76:79]
	v_mfma_f32_16x16x32_bf16 v[124:127], v[158:161], v[174:177], v[124:127]
	v_mfma_f32_16x16x32_bf16 v[120:123], v[166:169], v[174:177], v[120:123]
	v_mfma_f32_16x16x32_bf16 v[116:119], v[158:161], v[182:185], v[116:119]
	v_mfma_f32_16x16x32_bf16 v[108:111], v[166:169], v[182:185], v[108:111]
	v_mfma_f32_16x16x32_bf16 v[100:103], v[158:161], v[190:193], v[100:103]
	v_mfma_f32_16x16x32_bf16 v[92:95], v[166:169], v[190:193], v[92:95]
	v_mfma_f32_16x16x32_bf16 v[84:87], v[158:161], v[198:201], v[84:87]
	v_mfma_f32_16x16x32_bf16 v[76:79], v[166:169], v[198:201], v[76:79]
	s_barrier
	s_setprio 0
	s_add_i32 s82, s66, s56
	s_mov_b32 m0, s82
	s_nop 0
	global_load_lds_dwordx4 v136, s[46:47]
	s_add_i32 m0, s82, 0x2000
	s_nop 0
	global_load_lds_dwordx4 v140, s[46:47]
	s_waitcnt lgkmcnt(0)
	s_setprio 1
	s_barrier
	v_mfma_f32_16x16x32_bf16 v[112:115], v[202:205], v[170:173], v[112:115]
	v_mfma_f32_16x16x32_bf16 v[104:107], v[210:213], v[170:173], v[104:107]
	v_mfma_f32_16x16x32_bf16 v[96:99], v[202:205], v[178:181], v[96:99]
	v_mfma_f32_16x16x32_bf16 v[88:91], v[210:213], v[178:181], v[88:91]
	v_mfma_f32_16x16x32_bf16 v[80:83], v[202:205], v[186:189], v[80:83]
	v_mfma_f32_16x16x32_bf16 v[72:75], v[210:213], v[186:189], v[72:75]
	v_mfma_f32_16x16x32_bf16 v[68:71], v[202:205], v[194:197], v[68:71]
	v_mfma_f32_16x16x32_bf16 v[64:67], v[210:213], v[194:197], v[64:67]
	v_mfma_f32_16x16x32_bf16 v[112:115], v[206:209], v[174:177], v[112:115]
	ds_read_b128 v[170:173], v151 offset:16384
	v_mfma_f32_16x16x32_bf16 v[104:107], v[214:217], v[174:177], v[104:107]
	v_mfma_f32_16x16x32_bf16 v[96:99], v[206:209], v[182:185], v[96:99]
	ds_read_b128 v[178:181], v151 offset:18432
	v_mfma_f32_16x16x32_bf16 v[88:91], v[214:217], v[182:185], v[88:91]
	v_mfma_f32_16x16x32_bf16 v[80:83], v[206:209], v[190:193], v[80:83]
	ds_read_b128 v[186:189], v151 offset:20480
	v_mfma_f32_16x16x32_bf16 v[72:75], v[214:217], v[190:193], v[72:75]
	v_mfma_f32_16x16x32_bf16 v[68:71], v[206:209], v[198:201], v[68:71]
	ds_read_b128 v[194:197], v151 offset:22528
	v_mfma_f32_16x16x32_bf16 v[64:67], v[214:217], v[198:201], v[64:67]
	s_barrier
	s_setprio 0
	s_mov_b32 m0, s57
	s_mov_b64 s[100:101], s[48:49]
	global_load_lds_dwordx4 v134, s[48:49]
	s_mov_b32 m0, s58
	s_nop 0
	global_load_lds_dwordx4 v138, s[48:49]
	ds_read_b128 v[174:177], v151 offset:17408
	ds_read_b128 v[182:185], v151 offset:19456
	ds_read_b128 v[190:193], v151 offset:21504
	ds_read_b128 v[198:201], v151 offset:23552
	s_waitcnt vmcnt(8)
	s_waitcnt lgkmcnt(0)
	s_setprio 1
	s_barrier
	v_mfma_f32_16x16x32_bf16 v[60:63], v[154:157], v[170:173], v[60:63]
	v_mfma_f32_16x16x32_bf16 v[56:59], v[162:165], v[170:173], v[56:59]
	v_mfma_f32_16x16x32_bf16 v[52:55], v[154:157], v[178:181], v[52:55]
	v_mfma_f32_16x16x32_bf16 v[44:47], v[162:165], v[178:181], v[44:47]
	v_mfma_f32_16x16x32_bf16 v[36:39], v[154:157], v[186:189], v[36:39]
	v_mfma_f32_16x16x32_bf16 v[28:31], v[162:165], v[186:189], v[28:31]
	v_mfma_f32_16x16x32_bf16 v[20:23], v[154:157], v[194:197], v[20:23]
	v_mfma_f32_16x16x32_bf16 v[12:15], v[162:165], v[194:197], v[12:15]
	v_mfma_f32_16x16x32_bf16 v[60:63], v[158:161], v[174:177], v[60:63]
	v_mfma_f32_16x16x32_bf16 v[56:59], v[166:169], v[174:177], v[56:59]
	v_mfma_f32_16x16x32_bf16 v[52:55], v[158:161], v[182:185], v[52:55]
	v_mfma_f32_16x16x32_bf16 v[44:47], v[166:169], v[182:185], v[44:47]
	v_mfma_f32_16x16x32_bf16 v[36:39], v[158:161], v[190:193], v[36:39]
	v_mfma_f32_16x16x32_bf16 v[28:31], v[166:169], v[190:193], v[28:31]
	v_mfma_f32_16x16x32_bf16 v[20:23], v[158:161], v[198:201], v[20:23]
	v_mfma_f32_16x16x32_bf16 v[12:15], v[166:169], v[198:201], v[12:15]
	s_barrier
	s_setprio 0
	s_add_u32 s82, s46, 0x100000
	s_addc_u32 s83, s47, 0
	s_add_i32 s84, s67, s56
	s_mov_b32 m0, s84
	s_nop 0
	global_load_lds_dwordx4 v136, s[82:83]
	s_add_i32 m0, s84, 0x2000
	s_nop 0
	global_load_lds_dwordx4 v140, s[82:83]
	s_waitcnt vmcnt(6)
	s_setprio 1
	v_add_u32_e32 v153, 0x18000, v148
	s_barrier
; #define PG8_STAGE(bufoff, gbase, voff) do { _Pragma("unroll") for (int _i = 0; _i < 2; ++_i) \
;         __builtin_amdgcn_global_load_lds((const unsigned*)((const char*)(gbase) + (voff)[_i]), (LAS unsigned*)(lds + (bufoff) + ldsw + _i * 8192), 16, 0, 0); } while (0)
; #define PG8_LDA(dst, b, h) do { _Pragma("unroll") for (int m = 0; m < 4; ++m) _Pragma("unroll") for (int k = 0; k < 2; ++k) dst[m][k] = *(const LAS bf16x8*)(lds + PG8_SA(b, h) + aoff + m * 2048 + k * 1024); } while (0)
; #define PG8_LDB(dst, b, h) do { _Pragma("unroll") for (int n = 0; n < 2; ++n) _Pragma("unroll") for (int k = 0; k < 2; ++k) dst[n][k] = *(const LAS bf16x8*)(lds + PG8_SB(b, h) + boff + n * 2048 + k * 1024); } while (0)
; #define PG8_MMA(ai, bj, At, Bt) do { __builtin_amdgcn_s_setprio(1); _Pragma("unroll") for (int m = 0; m < 4; ++m) _Pragma("unroll") for (int n = 0; n < 2; ++n) _Pragma("unroll") for (int k = 0; k < 2; ++k) \
;         acc[ai][bj][m][n] = __builtin_amdgcn_mfma_f32_16x16x32_bf16(Bt[n][k], At[m][k], acc[ai][bj][m][n], 0, 0, 0); __builtin_amdgcn_s_setprio(0); } while (0)
; #define PG8_WAIT_V(n) asm volatile("s_waitcnt vmcnt(" #n ")" ::: "memory")
; #define PG8_WAIT_L(n) asm volatile("s_waitcnt lgkmcnt(" #n ")" ::: "memory")
; #define PG8_BAR __builtin_amdgcn_s_barrier()
; #define PG8_SCHED __builtin_amdgcn_sched_barrier(0)
; template <class Epi, class Job>
; __device__ __forceinline__ void gemm_phase(LAS unsigned char* lds, const Job& S, const Epi& E) {
;     ...
;             PG8_WAIT_V(6); PG8_BAR; PG8_MMA(1, 1, At, B1); PG8_BAR;
;             PG8_LDB(B0, 1, 0); PG8_SCHED; PG8_LDA(At, 1, 0); PG8_STAGE(PG8_SA(0, 1), a2 + hstepA, voffA);
;             PG8_WAIT_L(8); PG8_BAR; PG8_WAIT_L(0); PG8_MMA(0, 0, At, B0); PG8_BAR; PG8_SCHED;
;             PG8_LDB(B1, 1, 1); PG8_STAGE(PG8_SB(1, 0), b3, voffB);
;             PG8_BAR; PG8_WAIT_L(0); PG8_MMA(0, 1, At, B1); PG8_BAR;
;             PG8_LDA(At, 1, 1); PG8_STAGE(PG8_SA(1, 0), a3, voffA);
;             PG8_BAR; PG8_WAIT_L(0); PG8_MMA(1, 0, At, B0); PG8_BAR; PG8_SCHED;
	v_mfma_f32_16x16x32_bf16 v[48:51], v[202:205], v[170:173], v[48:51]
	ds_read_b128 v[154:157], v153
	v_mfma_f32_16x16x32_bf16 v[40:43], v[210:213], v[170:173], v[40:43]
	v_mfma_f32_16x16x32_bf16 v[32:35], v[202:205], v[178:181], v[32:35]
	ds_read_b128 v[158:161], v153 offset:1024
	v_mfma_f32_16x16x32_bf16 v[24:27], v[210:213], v[178:181], v[24:27]
	v_mfma_f32_16x16x32_bf16 v[16:19], v[202:205], v[186:189], v[16:19]
	ds_read_b128 v[162:165], v153 offset:2048
	v_mfma_f32_16x16x32_bf16 v[8:11], v[210:213], v[186:189], v[8:11]
	v_mfma_f32_16x16x32_bf16 v[4:7], v[202:205], v[194:197], v[4:7]
	ds_read_b128 v[166:169], v153 offset:3072
	v_mfma_f32_16x16x32_bf16 v[0:3], v[210:213], v[194:197], v[0:3]
	v_mfma_f32_16x16x32_bf16 v[48:51], v[206:209], v[174:177], v[48:51]
	ds_read_b128 v[170:173], v151 offset:32768
	v_mfma_f32_16x16x32_bf16 v[40:43], v[214:217], v[174:177], v[40:43]
	v_mfma_f32_16x16x32_bf16 v[32:35], v[206:209], v[182:185], v[32:35]
	ds_read_b128 v[178:181], v151 offset:34816
	v_mfma_f32_16x16x32_bf16 v[24:27], v[214:217], v[182:185], v[24:27]
	v_mfma_f32_16x16x32_bf16 v[16:19], v[206:209], v[190:193], v[16:19]
	ds_read_b128 v[186:189], v151 offset:36864
	v_mfma_f32_16x16x32_bf16 v[8:11], v[214:217], v[190:193], v[8:11]
	v_mfma_f32_16x16x32_bf16 v[4:7], v[206:209], v[198:201], v[4:7]
	ds_read_b128 v[194:197], v151 offset:38912
	v_mfma_f32_16x16x32_bf16 v[0:3], v[214:217], v[198:201], v[0:3]
	s_barrier
	s_setprio 0
	s_add_i32 s82, 0, 0x18000
	v_add_u32_e32 v153, s82, v148
	s_add_u32 s48, s48, 0x100000
	s_addc_u32 s49, s49, 0
	s_mov_b32 m0, s59
	s_nop 0
	global_load_lds_dwordx4 v134, s[48:49]
	s_mov_b32 m0, s60
	s_nop 0
	global_load_lds_dwordx4 v138, s[48:49]
	ds_read_b128 v[174:177], v151 offset:33792
	ds_read_b128 v[182:185], v151 offset:35840
	ds_read_b128 v[190:193], v151 offset:37888
	ds_read_b128 v[198:201], v151 offset:39936
	s_waitcnt lgkmcnt(8)
	s_waitcnt lgkmcnt(0)
	s_setprio 1
	v_add_u32_e32 v153, 0x1c000, v148
	s_barrier
	v_mfma_f32_16x16x32_bf16 v[124:127], v[154:157], v[170:173], v[124:127]
	ds_read_b128 v[202:205], v153
	v_mfma_f32_16x16x32_bf16 v[120:123], v[162:165], v[170:173], v[120:123]
	v_mfma_f32_16x16x32_bf16 v[116:119], v[154:157], v[178:181], v[116:119]
	ds_read_b128 v[206:209], v153 offset:1024
	v_mfma_f32_16x16x32_bf16 v[108:111], v[162:165], v[178:181], v[108:111]
	v_mfma_f32_16x16x32_bf16 v[100:103], v[154:157], v[186:189], v[100:103]
	ds_read_b128 v[210:213], v153 offset:2048
	v_mfma_f32_16x16x32_bf16 v[92:95], v[162:165], v[186:189], v[92:95]
	v_mfma_f32_16x16x32_bf16 v[84:87], v[154:157], v[194:197], v[84:87]
	ds_read_b128 v[214:217], v153 offset:3072
	v_mfma_f32_16x16x32_bf16 v[76:79], v[162:165], v[194:197], v[76:79]
	v_mfma_f32_16x16x32_bf16 v[124:127], v[158:161], v[174:177], v[124:127]
	v_mfma_f32_16x16x32_bf16 v[120:123], v[166:169], v[174:177], v[120:123]
	v_mfma_f32_16x16x32_bf16 v[116:119], v[158:161], v[182:185], v[116:119]
	v_mfma_f32_16x16x32_bf16 v[108:111], v[166:169], v[182:185], v[108:111]
	v_mfma_f32_16x16x32_bf16 v[100:103], v[158:161], v[190:193], v[100:103]
	v_mfma_f32_16x16x32_bf16 v[92:95], v[166:169], v[190:193], v[92:95]
	v_mfma_f32_16x16x32_bf16 v[84:87], v[158:161], v[198:201], v[84:87]
	v_mfma_f32_16x16x32_bf16 v[76:79], v[166:169], v[198:201], v[76:79]
	s_barrier
	s_setprio 0
	s_add_i32 s48, 0, 0x1c000
	s_add_i32 s49, s82, s56
	v_add_u32_e32 v153, s48, v148
	s_add_u32 s98, s46, s8
	s_addc_u32 s99, s47, s9
	s_mov_b32 m0, s49
	s_nop 0
	global_load_lds_dwordx4 v136, s[98:99]
	s_add_i32 m0, s49, 0x2000
	s_nop 0
	global_load_lds_dwordx4 v140, s[98:99]
	s_waitcnt lgkmcnt(0)
	s_setprio 1
	s_barrier
	v_mfma_f32_16x16x32_bf16 v[112:115], v[202:205], v[170:173], v[112:115]
	v_mfma_f32_16x16x32_bf16 v[104:107], v[210:213], v[170:173], v[104:107]
	v_mfma_f32_16x16x32_bf16 v[96:99], v[202:205], v[178:181], v[96:99]
	v_mfma_f32_16x16x32_bf16 v[88:91], v[210:213], v[178:181], v[88:91]
	v_mfma_f32_16x16x32_bf16 v[80:83], v[202:205], v[186:189], v[80:83]
	v_mfma_f32_16x16x32_bf16 v[72:75], v[210:213], v[186:189], v[72:75]
	v_mfma_f32_16x16x32_bf16 v[68:71], v[202:205], v[194:197], v[68:71]
	v_mfma_f32_16x16x32_bf16 v[64:67], v[210:213], v[194:197], v[64:67]
	v_mfma_f32_16x16x32_bf16 v[112:115], v[206:209], v[174:177], v[112:115]
	ds_read_b128 v[170:173], v151 offset:49152
	v_mfma_f32_16x16x32_bf16 v[104:107], v[214:217], v[174:177], v[104:107]
	v_mfma_f32_16x16x32_bf16 v[96:99], v[206:209], v[182:185], v[96:99]
	ds_read_b128 v[178:181], v151 offset:51200
	v_mfma_f32_16x16x32_bf16 v[88:91], v[214:217], v[182:185], v[88:91]
	v_mfma_f32_16x16x32_bf16 v[80:83], v[206:209], v[190:193], v[80:83]
	ds_read_b128 v[186:189], v151 offset:53248
	v_mfma_f32_16x16x32_bf16 v[72:75], v[214:217], v[190:193], v[72:75]
	v_mfma_f32_16x16x32_bf16 v[68:71], v[206:209], v[198:201], v[68:71]
	ds_read_b128 v[194:197], v151 offset:55296
	v_mfma_f32_16x16x32_bf16 v[64:67], v[214:217], v[198:201], v[64:67]
	s_barrier
	s_setprio 0
	s_mov_b32 m0, s62
	s_add_u32 s100, s100, s8
	s_addc_u32 s101, s101, s9
	global_load_lds_dwordx4 v134, s[100:101]
	s_mov_b32 m0, s63
	s_nop 0
	global_load_lds_dwordx4 v138, s[100:101]
	ds_read_b128 v[174:177], v151 offset:50176
	ds_read_b128 v[182:185], v151 offset:52224
	ds_read_b128 v[190:193], v151 offset:54272
	ds_read_b128 v[198:201], v151 offset:56320
	s_waitcnt vmcnt(8)
	s_waitcnt lgkmcnt(0)
	s_setprio 1
	s_barrier
; #define PG8_STAGE(bufoff, gbase, voff) do { _Pragma("unroll") for (int _i = 0; _i < 2; ++_i) \
;         __builtin_amdgcn_global_load_lds((const unsigned*)((const char*)(gbase) + (voff)[_i]), (LAS unsigned*)(lds + (bufoff) + ldsw + _i * 8192), 16, 0, 0); } while (0)
; #define PG8_MMA(ai, bj, At, Bt) do { __builtin_amdgcn_s_setprio(1); _Pragma("unroll") for (int m = 0; m < 4; ++m) _Pragma("unroll") for (int n = 0; n < 2; ++n) _Pragma("unroll") for (int k = 0; k < 2; ++k) \
;         acc[ai][bj][m][n] = __builtin_amdgcn_mfma_f32_16x16x32_bf16(Bt[n][k], At[m][k], acc[ai][bj][m][n], 0, 0, 0); __builtin_amdgcn_s_setprio(0); } while (0)
; #define PG8_WAIT_V(n) asm volatile("s_waitcnt vmcnt(" #n ")" ::: "memory")
; #define PG8_WAIT_L(n) asm volatile("s_waitcnt lgkmcnt(" #n ")" ::: "memory")
; #define PG8_BAR __builtin_amdgcn_s_barrier()
; #define PG8_SCHED __builtin_amdgcn_sched_barrier(0)
; template <class Epi, class Job>
; __device__ __forceinline__ void gemm_phase(LAS unsigned char* lds, const Job& S, const Epi& E) {
;     ...
;             PG8_BAR; PG8_WAIT_L(0); PG8_MMA(1, 0, At, B0); PG8_BAR; PG8_SCHED;
;             PG8_STAGE(PG8_SB(1, 1), b3 + hstepB, voffB);
;             PG8_WAIT_V(6); PG8_BAR; PG8_MMA(1, 1, At, B1); PG8_BAR;
;         }
	v_mfma_f32_16x16x32_bf16 v[60:63], v[154:157], v[170:173], v[60:63]
	v_mfma_f32_16x16x32_bf16 v[56:59], v[162:165], v[170:173], v[56:59]
	v_mfma_f32_16x16x32_bf16 v[52:55], v[154:157], v[178:181], v[52:55]
	v_mfma_f32_16x16x32_bf16 v[44:47], v[162:165], v[178:181], v[44:47]
	v_mfma_f32_16x16x32_bf16 v[36:39], v[154:157], v[186:189], v[36:39]
	v_mfma_f32_16x16x32_bf16 v[28:31], v[162:165], v[186:189], v[28:31]
	v_mfma_f32_16x16x32_bf16 v[20:23], v[154:157], v[194:197], v[20:23]
	v_mfma_f32_16x16x32_bf16 v[12:15], v[162:165], v[194:197], v[12:15]
	v_mfma_f32_16x16x32_bf16 v[60:63], v[158:161], v[174:177], v[60:63]
	v_mfma_f32_16x16x32_bf16 v[56:59], v[166:169], v[174:177], v[56:59]
	v_mfma_f32_16x16x32_bf16 v[52:55], v[158:161], v[182:185], v[52:55]
	v_mfma_f32_16x16x32_bf16 v[44:47], v[166:169], v[182:185], v[44:47]
	v_mfma_f32_16x16x32_bf16 v[36:39], v[158:161], v[190:193], v[36:39]
	v_mfma_f32_16x16x32_bf16 v[28:31], v[166:169], v[190:193], v[28:31]
	v_mfma_f32_16x16x32_bf16 v[20:23], v[158:161], v[198:201], v[20:23]
	v_mfma_f32_16x16x32_bf16 v[12:15], v[166:169], v[198:201], v[12:15]
	s_barrier
	s_setprio 0
	s_add_u32 s46, s46, 0x100080
	s_addc_u32 s47, s47, 0
	s_add_i32 s48, s48, s56
	s_mov_b32 m0, s48
	s_nop 0
	global_load_lds_dwordx4 v136, s[46:47]
	s_add_i32 m0, s48, 0x2000
	s_nop 0
	global_load_lds_dwordx4 v140, s[46:47]
	s_waitcnt vmcnt(6)
	s_setprio 1
	s_barrier
	v_mfma_f32_16x16x32_bf16 v[48:51], v[202:205], v[170:173], v[48:51]
	ds_read_b128 v[154:157], v150
	v_mfma_f32_16x16x32_bf16 v[40:43], v[210:213], v[170:173], v[40:43]
	v_mfma_f32_16x16x32_bf16 v[32:35], v[202:205], v[178:181], v[32:35]
	ds_read_b128 v[158:161], v150 offset:1024
	v_mfma_f32_16x16x32_bf16 v[24:27], v[210:213], v[178:181], v[24:27]
	v_mfma_f32_16x16x32_bf16 v[16:19], v[202:205], v[186:189], v[16:19]
	ds_read_b128 v[162:165], v150 offset:2048
	v_mfma_f32_16x16x32_bf16 v[8:11], v[210:213], v[186:189], v[8:11]
	v_mfma_f32_16x16x32_bf16 v[4:7], v[202:205], v[194:197], v[4:7]
	ds_read_b128 v[166:169], v150 offset:3072
	v_mfma_f32_16x16x32_bf16 v[0:3], v[210:213], v[194:197], v[0:3]
	v_mfma_f32_16x16x32_bf16 v[48:51], v[206:209], v[174:177], v[48:51]
	ds_read_b128 v[170:173], v151
	v_mfma_f32_16x16x32_bf16 v[40:43], v[214:217], v[174:177], v[40:43]
	v_mfma_f32_16x16x32_bf16 v[32:35], v[206:209], v[182:185], v[32:35]
	ds_read_b128 v[178:181], v151 offset:2048
	v_mfma_f32_16x16x32_bf16 v[24:27], v[214:217], v[182:185], v[24:27]
	v_mfma_f32_16x16x32_bf16 v[16:19], v[206:209], v[190:193], v[16:19]
	ds_read_b128 v[186:189], v151 offset:4096
	v_mfma_f32_16x16x32_bf16 v[8:11], v[214:217], v[190:193], v[8:11]
	v_mfma_f32_16x16x32_bf16 v[4:7], v[206:209], v[198:201], v[4:7]
	ds_read_b128 v[194:197], v151 offset:6144
	v_mfma_f32_16x16x32_bf16 v[0:3], v[214:217], v[198:201], v[0:3]
	s_barrier
	s_setprio 0
	s_add_i32 s81, s81, 2
	s_add_u32 s36, s36, 0x100
	s_addc_u32 s37, s37, 0
	s_add_u32 s79, s79, 0x100
	s_addc_u32 s80, s80, 0
	s_cmp_gt_u32 s81, 61
	s_cbranch_scc0 .LBB0_457
; __device__ __forceinline__ unsigned cvt_pk_bf16(float lo, float hi) { unsigned r; asm volatile("v_cvt_pk_bf16_f32 %0, %1, %2" : "=v"(r) : "v"(lo), "v"(hi)); return r; }
;     __device__ __forceinline__ void operator()(const f32x4 (&acc)[2][2][4][2], const Unit& u, int wr, int wc, int fr, int fq) const {
;         const int row0 = u.orow + wr * 64 + fr, col0 = u.ocol + wc * 32 + 8 * fq;
; #pragma unroll
;         for (int ai = 0; ai < 2; ++ai)
; #pragma unroll
;             for (int m = 0; m < 4; ++m) { bf16_t* rowp = O + (size_t)(row0 + ai * HALF + m * 16) * ldc + col0;
; #pragma unroll
;                 for (int bj = 0; bj < 2; ++bj) { const f32x4 v0 = acc[ai][bj][m][0], v1 = acc[ai][bj][m][1];
;                     u32x4 w; w.x = cvt_pk_bf16(v0[0], v0[1]); w.y = cvt_pk_bf16(v0[2], v0[3]); w.z = cvt_pk_bf16(v1[0], v1[1]); w.w = cvt_pk_bf16(v1[2], v1[3]);
;                     if (nt) __builtin_nontemporal_store(w, (u32x4*)(rowp + bj * HALF)); else *(u32x4*)(rowp + bj * HALF) = w; } }
	s_waitcnt lgkmcnt(0)
	v_add_u32_e32 v146, s78, v131
	v_ashrrev_i32_e32 v147, 31, v146
	v_add_u32_e32 v154, s77, v149
	v_lshlrev_b64 v[146:147], 13, v[146:147]
	v_ashrrev_i32_e32 v155, 31, v154
	v_lshl_add_u64 v[146:147], s[18:19], 0, v[146:147]
	v_lshl_add_u64 v[146:147], v[154:155], 1, v[146:147]
	v_cvt_pk_bf16_f32 v124, v124, v125
	v_cvt_pk_bf16_f32 v125, v126, v127
	v_cvt_pk_bf16_f32 v126, v120, v121
	v_cvt_pk_bf16_f32 v127, v122, v123
	global_store_dwordx4 v[146:147], v[124:127], off
	v_cvt_pk_bf16_f32 v112, v112, v113
	v_cvt_pk_bf16_f32 v113, v114, v115
	v_cvt_pk_bf16_f32 v114, v104, v105
	v_cvt_pk_bf16_f32 v115, v106, v107
	global_store_dwordx4 v[146:147], v[112:115], off offset:256
	v_cvt_pk_bf16_f32 v104, v116, v117
	v_cvt_pk_bf16_f32 v105, v118, v119
	v_cvt_pk_bf16_f32 v106, v108, v109
	v_add_co_u32_e32 v108, vcc, s68, v146
	s_nop 0
	v_lshl_add_u64 v[112:113], v[146:147], 0, s[10:11]
	v_addc_co_u32_e32 v109, vcc, 0, v147, vcc
	v_cvt_pk_bf16_f32 v107, v110, v111
	global_store_dwordx4 v[108:109], v[104:107], off
	v_cvt_pk_bf16_f32 v96, v96, v97
	v_cvt_pk_bf16_f32 v97, v98, v99
	v_cvt_pk_bf16_f32 v98, v88, v89
	v_cvt_pk_bf16_f32 v99, v90, v91
	global_store_dwordx4 v[112:113], v[96:99], off offset:256
	v_cvt_pk_bf16_f32 v88, v100, v101
	v_cvt_pk_bf16_f32 v89, v102, v103
	v_cvt_pk_bf16_f32 v90, v92, v93
	v_add_co_u32_e32 v92, vcc, s69, v146
	s_nop 0
	v_lshl_add_u64 v[96:97], v[146:147], 0, s[12:13]
	v_addc_co_u32_e32 v93, vcc, 0, v147, vcc
	v_cvt_pk_bf16_f32 v91, v94, v95
	global_store_dwordx4 v[92:93], v[88:91], off
	v_cvt_pk_bf16_f32 v80, v80, v81
	v_cvt_pk_bf16_f32 v81, v82, v83
	v_cvt_pk_bf16_f32 v82, v72, v73
	v_cvt_pk_bf16_f32 v83, v74, v75
	global_store_dwordx4 v[96:97], v[80:83], off offset:256
	v_cvt_pk_bf16_f32 v72, v84, v85
	v_cvt_pk_bf16_f32 v73, v86, v87
	v_cvt_pk_bf16_f32 v74, v76, v77
	v_add_co_u32_e32 v76, vcc, s70, v146
	s_nop 0
	v_lshl_add_u64 v[80:81], v[146:147], 0, s[20:21]
	v_addc_co_u32_e32 v77, vcc, 0, v147, vcc
	v_cvt_pk_bf16_f32 v75, v78, v79
	global_store_dwordx4 v[76:77], v[72:75], off
	v_cvt_pk_bf16_f32 v68, v68, v69
	v_cvt_pk_bf16_f32 v69, v70, v71
	v_cvt_pk_bf16_f32 v70, v64, v65
	v_cvt_pk_bf16_f32 v71, v66, v67
	global_store_dwordx4 v[80:81], v[68:71], off offset:256
	v_cvt_pk_bf16_f32 v60, v60, v61
	v_cvt_pk_bf16_f32 v61, v62, v63
	v_cvt_pk_bf16_f32 v62, v56, v57
	v_add_co_u32_e32 v56, vcc, s71, v146
	v_lshl_add_u64 v[64:65], v[146:147], 0, s[6:7]
	s_nop 0
	v_addc_co_u32_e32 v57, vcc, 0, v147, vcc
	v_cvt_pk_bf16_f32 v63, v58, v59
	global_store_dwordx4 v[56:57], v[60:63], off
	v_cvt_pk_bf16_f32 v48, v48, v49
	v_cvt_pk_bf16_f32 v49, v50, v51
	v_cvt_pk_bf16_f32 v50, v40, v41
	v_cvt_pk_bf16_f32 v51, v42, v43
	global_store_dwordx4 v[64:65], v[48:51], off offset:256
	v_cvt_pk_bf16_f32 v40, v52, v53
	v_cvt_pk_bf16_f32 v41, v54, v55
	v_cvt_pk_bf16_f32 v42, v44, v45
	v_add_co_u32_e32 v44, vcc, s72, v146
	s_nop 0
	v_lshl_add_u64 v[48:49], v[146:147], 0, s[22:23]
	v_addc_co_u32_e32 v45, vcc, 0, v147, vcc
	v_cvt_pk_bf16_f32 v43, v46, v47
	global_store_dwordx4 v[44:45], v[40:43], off
	v_cvt_pk_bf16_f32 v32, v32, v33
	v_cvt_pk_bf16_f32 v33, v34, v35
	v_cvt_pk_bf16_f32 v34, v24, v25
	v_cvt_pk_bf16_f32 v35, v26, v27
	global_store_dwordx4 v[48:49], v[32:35], off offset:256
	v_cvt_pk_bf16_f32 v24, v36, v37
	v_cvt_pk_bf16_f32 v25, v38, v39
	v_cvt_pk_bf16_f32 v26, v28, v29
	v_add_co_u32_e32 v28, vcc, s73, v146
	s_nop 0
	v_lshl_add_u64 v[32:33], v[146:147], 0, s[24:25]
	v_addc_co_u32_e32 v29, vcc, 0, v147, vcc
	v_cvt_pk_bf16_f32 v27, v30, v31
	global_store_dwordx4 v[28:29], v[24:27], off
	v_cvt_pk_bf16_f32 v16, v16, v17
	v_cvt_pk_bf16_f32 v17, v18, v19
	v_cvt_pk_bf16_f32 v18, v8, v9
	v_cvt_pk_bf16_f32 v19, v10, v11
	global_store_dwordx4 v[32:33], v[16:19], off offset:256
	v_cvt_pk_bf16_f32 v8, v20, v21
	v_cvt_pk_bf16_f32 v9, v22, v23
	v_cvt_pk_bf16_f32 v10, v12, v13
	v_add_co_u32_e32 v12, vcc, s74, v146
	s_nop 0
	v_lshl_add_u64 v[16:17], v[146:147], 0, s[26:27]
	v_addc_co_u32_e32 v13, vcc, 0, v147, vcc
	s_and_b64 vcc, exec, s[4:5]
	s_mov_b32 s77, s76
	s_mov_b32 s78, s75
	s_mov_b64 s[46:47], s[30:31]
	s_mov_b64 s[36:37], s[28:29]
	v_cvt_pk_bf16_f32 v11, v14, v15
	global_store_dwordx4 v[12:13], v[8:11], off
	v_cvt_pk_bf16_f32 v4, v4, v5
	v_cvt_pk_bf16_f32 v5, v6, v7
	v_cvt_pk_bf16_f32 v6, v0, v1
	v_cvt_pk_bf16_f32 v7, v2, v3
	global_store_dwordx4 v[16:17], v[4:7], off offset:256
	s_cbranch_vccz .LBB0_450
	s_waitcnt vmcnt(0)
	s_cmpk_gt_u32 s50, 0xff
	s_cbranch_scc1 .LBB0_461
	s_barrier
